# hgrn unit loops: workspace / norm-weight pointers read once in the pre-header instead of s_load + wait every unit
# speedup vs baseline: 1.0074x; 1.0014x over previous
; template <int WHICH>
; __device__ __forceinline__ HgRaw hg_load(KP& P_, int l, int u, int tid) {
;     const bf16_t* proj = (const bf16_t*)(p.ws + WS_PROJ);
;     const int idx = u - 780, bc = idx / 6, h = idx - bc * 6, t = tid >> 3, k0 = (tid & 7) * 8; const size_t row = (size_t)bc * 64 + t;
;     HgRaw r; r.q = (u32x4){0u, 0u, 0u, 0u};
;     if (WHICH) r.q = *(const u32x4*)(proj + row * NPROJ + h * 64 + k0);
;     r.f = *(const u32x4*)(proj + row * NPROJ + C_F + h * 64 + k0);
;     r.i = *(const u32x4*)(proj + row * NPROJ + C_I + h * 64 + k0);
;     const float* lbv = (const float*)(p.ws + TBL(T_LB, l)) + h * 64 + k0; r.lb0 = *(const f32x4*)lbv; r.lb1 = *(const f32x4*)(lbv + 4);
;     return r;
; template <int WHICH>
; __device__ void phase_mix_dyn(LAS unsigned char* lds, KP& P0, int l0) {
;     ...
;     HgRaw nxt; { KPtr P_ = P0; asm volatile("" : "+s"(P_.q)); nxt = hg_load<WHICH>(P_, l0, u, tid0); }
.LBB0_479:
	s_cmpk_gt_u32 s20, 0x923
	s_cbranch_scc1 .LBB0_502
	s_mov_b64 s[6:7], s[30:31]
	s_load_dwordx2 s[6:7], s[6:7], 0xe8
	s_add_i32 s12, s20, 0xfffffcf4
	s_mul_i32 s13, s12, 0xaaab
	s_lshr_b32 s13, s13, 18
	v_ashrrev_i32_e32 v2, 3, v138
	v_lshlrev_b32_e32 v0, 3, v138
	s_mul_i32 s14, s13, -6
	s_waitcnt vmcnt(0)
	v_and_b32_e32 v72, 56, v0
	v_lshl_add_u32 v0, s13, 6, v2
	s_waitcnt lgkmcnt(0)
	v_mov_b64_e32 v[8:9], s[6:7]
	s_add_i32 s14, s14, s12
	v_mad_i64_i32 v[8:9], s[12:13], v0, s9, v[8:9]
	s_lshl_b32 s12, s14, 6
	v_readlane_b32 s14, v255, 25
	v_readlane_b32 s15, v255, 26
	s_mov_b32 s22, s14
	s_ashr_i32 s13, s12, 31
	s_mul_i32 s15, s22, 0x44800
	s_mul_hi_i32 s14, s14, 0x44800
	s_add_u32 s15, s6, s15
	s_addc_u32 s14, s7, s14
	s_lshl_b64 s[6:7], s[12:13], 2
	v_lshl_add_u64 v[8:9], s[12:13], 1, v[8:9]
	v_lshlrev_b32_e32 v0, 1, v72
	s_add_u32 s6, s15, s6
	v_lshl_add_u64 v[8:9], v[8:9], 0, v[0:1]
	s_addc_u32 s7, s14, s7
	v_lshlrev_b32_e32 v0, 2, v72
	global_load_dwordx4 v[52:55], v[8:9], off
	global_load_dwordx4 v[68:71], v[8:9], off offset:768
	global_load_dwordx4 v[56:59], v[8:9], off offset:1536
	v_lshl_add_u64 v[8:9], s[6:7], 0, v[0:1]
	s_mov_b64 s[6:7], 0xef04800
	v_lshl_add_u64 v[10:11], v[8:9], 0, s[6:7]
	v_add_co_u32_e32 v8, vcc, 0xef04000, v8
	v_ashrrev_i32_e32 v3, 31, v2
	s_nop 0
	v_addc_co_u32_e32 v9, vcc, 0, v9, vcc
	global_load_dwordx4 v[64:67], v[8:9], off offset:2048
	global_load_dwordx4 v[60:63], v[10:11], off offset:16
	s_waitcnt vmcnt(0)
	s_load_dwordx2 s[72:73], s[30:31], 0xe8
	s_load_dwordx2 s[74:75], s[30:31], 0x20
	s_waitcnt lgkmcnt(0)
	s_branch .LBB0_483

; template <int WHICH>
; __device__ void phase_mix_dyn(LAS unsigned char* lds, KP& P0, int l0) {
;     ...
;     for (;;) {
;         if (tid0 == 0) { n1 = n2; n2 = (int)__hip_atomic_fetch_add(ctr, 1u, __ATOMIC_RELAXED, __HIP_MEMORY_SCOPE_AGENT); }
;         KPtr P_ = P0; int l = l0; asm volatile("" : "+s"(P_.q), "+s"(l));
;         const HgRaw cur = nxt;
;         if (un < NMIXU) nxt = hg_load<WHICH>(P_, l, un, tid0);
.LBB0_483:
	v_readlane_b32 s6, v255, 25
	s_mov_b32 s12, s6
	s_mov_b64 s[46:47], s[30:31]
	s_mov_b64 s[42:43], s[72:73]
	s_cmpk_lt_i32 s21, 0x924
	v_readlane_b32 s7, v255, 26
	s_cselect_b64 s[24:25], -1, 0
	s_cmpk_gt_i32 s21, 0x923
	s_cselect_b64 s[6:7], -1, 0
	v_mov_b64_e32 v[8:9], v[52:53]
	v_mov_b64_e32 v[12:13], v[68:69]
	v_mov_b64_e32 v[20:21], v[56:57]
	v_mov_b64_e32 v[16:17], v[64:65]
	s_and_saveexec_b64 s[14:15], s[40:41]
	s_cbranch_execz .Lhg_tk_c
	v_mov_b32_e32 v137, v136
	v_readlane_b32 s22, v255, 30
	v_readlane_b32 s23, v255, 31
	s_nop 4
	global_atomic_add v136, v1, v203, s[22:23] sc0

; #define LAS __attribute__((address_space(3)))
; __device__ __forceinline__ void unpack8(const u32x4 v, float* o) { o[0] = bflo(v.x); o[1] = bfhi(v.x); o[2] = bflo(v.y); o[3] = bfhi(v.y); o[4] = bflo(v.z); o[5] = bfhi(v.z); o[6] = bflo(v.w); o[7] = bfhi(v.w); }
; __device__ __forceinline__ float siluf_(float x) { return x * __builtin_amdgcn_rcpf(1.0f + __expf(-x)); }
; __device__ __forceinline__ int tidx() { int t = threadIdx.x; asm volatile("" : "+v"(t)); return t; }
; __device__ __forceinline__ void hgrn_c_unit(LAS unsigned char* lds, KP& P_, int l, int bc, int h, const HgRaw& in) {
;     LAS float* Gf = (LAS float*)lds; LAS float* seg = (LAS float*)(lds + 16640);
;     LAS bf16_t* QP = (LAS bf16_t*)(lds + 18688); LAS bf16_t* QPP = (LAS bf16_t*)(lds + 27904); LAS bf16_t* KP = (LAS bf16_t*)(lds + 37120);
;     LAS bf16_t* VT = (LAS bf16_t*)(lds + 46336); LAS bf16_t* PM = (LAS bf16_t*)(lds + 55552); LAS float* ss = (LAS float*)(lds + 64768);
;     const bf16_t* proj = (const bf16_t*)(p.ws + WS_PROJ); const float* lbv = (const float*)(p.ws + TBL(T_LB, l));
;     const int tid = tidx(), t = tid >> 3, k0 = (tid & 7) * 8; const size_t row = (size_t)bc * 64 + t;
;     const int wid = tid >> 6, lane = tid & 63, fr = lane & 15, fq = lane >> 4;
;     float z[8], q[8], lf[8], kk[8], lb[8];
;     const int tt2 = wid & 3, vh = wid >> 2;
;     bf16x8 sf[2][2]; u32x2 graw[2];
;     { const bf16_t* sth = (const bf16_t*)(p.ws + WS_STH) + ((size_t)bc * 6 + h) * 4096;
; #pragma unroll
;       for (int qq = 0; qq < 2; ++qq) { const int vt = vh * 2 + qq;
; #pragma unroll
;           for (int ks = 0; ks < 2; ++ks) sf[qq][ks] = *(const bf16x8*)(sth + (size_t)(vt * 16 + fr) * 64 + ks * 32 + fq * 8);
;           graw[qq] = *(const u32x2*)(proj + ((size_t)bc * 64 + tt2 * 16 + fr) * NPROJ + C_G + h * 64 + vt * 16 + fq * 4); } }
;     f32x4 nwv[2];
; #pragma unroll
;     for (int qq = 0; qq < 2; ++qq) nwv[qq] = *(const f32x4*)(p.in[4] + l * 64 + (vh * 2 + qq) * 16 + fq * 4);
;     unpack8(in.q, q);
;     unpack8(in.f, z);
;     const u32x4 iraw = in.i;
; #pragma unroll
;     for (int j = 0; j < 8; ++j) { lb[j] = j < 4 ? in.lb0[j & 3] : in.lb1[j & 3]; q[j] = siluf_(q[j]); }
;     hgrn_gates(z, lb, lf, kk);
;     {
; #pragma unroll
;       for (int j = 0; j < 8; ++j) Gf[t * 65 + k0 + j] = lf[j];
;       *(LAS u32x4*)(VT + t * 72 + k0) = iraw; }
;     LBAR();
;     cumsum64(Gf, seg);
.LBB0_489:
	s_add_i32 s13, s20, 0xfffffcf4
	s_mul_hi_i32 s14, s13, 0x2aaaaaab
	s_lshr_b32 s15, s14, 31
	s_add_i32 s14, s14, s15
	s_mul_i32 s26, s14, 6
	s_sub_i32 s13, s13, s26
	s_ashr_i32 s15, s14, 31
	s_lshl_b64 s[22:23], s[14:15], 6
	s_ashr_i32 s44, s13, 31
	s_mul_hi_i32 s15, s14, 6
	s_add_u32 s14, s26, s13
	v_mov_b32_e32 v95, v198
	s_addc_u32 s15, s15, s44
	s_lshl_b64 s[14:15], s[14:15], 13
	v_ashrrev_i32_e32 v96, 6, v95
	v_and_b32_e32 v73, 15, v95
	v_bfe_u32 v92, v95, 4, 2
	v_and_b32_e32 v91, 3, v96
	v_ashrrev_i32_e32 v90, 8, v95
	s_waitcnt lgkmcnt(0)
	s_add_u32 s14, s42, s14
	s_addc_u32 s15, s43, s15
	v_lshlrev_b32_e32 v80, 5, v90
	v_lshlrev_b32_e32 v28, 4, v92
	v_mov_b32_e32 v29, v1
	v_lshl_or_b32 v93, v91, 4, v73
	v_lshl_add_u64 v[30:31], s[14:15], 0, v[28:29]
	s_mov_b64 s[14:15], 0xc300000
	v_or_b32_e32 v78, s22, v93
	v_mov_b64_e32 v[32:33], s[42:43]
	v_or_b32_e32 v34, v80, v73
	v_lshl_add_u64 v[30:31], v[30:31], 0, s[14:15]
	v_mad_u64_u32 v[32:33], s[14:15], v78, s9, v[32:33]
	s_lshl_b32 s44, s13, 6
	v_ashrrev_i32_e32 v35, 31, v34
	v_mad_i32_i24 v33, s23, v215, v33
	s_ashr_i32 s45, s44, 31
	v_lshlrev_b64 v[36:37], 7, v[34:35]
	v_or_b32_e32 v34, 16, v34
	v_lshlrev_b32_e32 v0, 3, v92
	v_lshl_add_u64 v[32:33], s[44:45], 1, v[32:33]
	v_ashrrev_i32_e32 v35, 31, v34
	v_lshl_add_u64 v[32:33], v[32:33], 0, v[0:1]
	v_ashrrev_i32_e32 v81, 31, v80
	v_lshlrev_b64 v[34:35], 7, v[34:35]
	v_lshl_add_u64 v[36:37], v[30:31], 0, v[36:37]
	v_lshl_add_u64 v[32:33], v[80:81], 1, v[32:33]
	v_lshl_add_u64 v[30:31], v[30:31], 0, v[34:35]
	global_load_dwordx4 v[48:51], v[36:37], off
	global_load_dwordx4 v[44:47], v[36:37], off offset:64
	global_load_dwordx2 v[76:77], v[32:33], off offset:2304
	global_load_dwordx4 v[40:43], v[30:31], off
	s_nop 0
	global_load_dwordx4 v[36:39], v[30:31], off offset:64
	global_load_dwordx2 v[74:75], v[32:33], off offset:2336
	s_mov_b64 s[14:15], s[74:75]
	s_lshl_b32 s12, s12, 6
	s_ashr_i32 s13, s12, 31
	s_lshl_b64 s[12:13], s[12:13], 2
	v_and_b32_e32 v82, 0xffff0000, v68
	s_waitcnt lgkmcnt(0)
	s_add_u32 s12, s14, s12
	s_addc_u32 s13, s15, s13
	v_lshl_add_u64 v[28:29], s[12:13], 0, v[28:29]
	v_lshl_add_u64 v[28:29], v[80:81], 2, v[28:29]
	v_lshlrev_b32_e32 v81, 16, v68
	v_mul_f32_e32 v68, 0xbfb8aa3b, v81
	v_lshlrev_b32_e32 v83, 16, v69
	v_and_b32_e32 v84, 0xffff0000, v69
	v_exp_f32_e32 v68, v68
	v_mul_f32_e32 v69, 0xbfb8aa3b, v82
	v_exp_f32_e32 v69, v69
	global_load_dwordx4 v[32:35], v[28:29], off
	s_nop 0
	global_load_dwordx4 v[28:31], v[28:29], off offset:64
	v_add_f32_e32 v68, 1.0, v68
	v_rcp_f32_e32 v68, v68
	v_add_f32_e32 v69, 1.0, v69
	v_rcp_f32_e32 v69, v69
	v_lshlrev_b32_e32 v85, 16, v70
	v_and_b32_e32 v86, 0xffff0000, v70
	v_lshlrev_b32_e32 v87, 16, v71
	v_and_b32_e32 v89, 0xffff0000, v71
	v_pk_add_f32 v[70:71], v[64:65], 1.0 op_sel_hi:[1,0] neg_lo:[1,0] neg_hi:[1,0]
	v_lshlrev_b32_e32 v94, 3, v95
	v_fma_f32 v64, v70, v68, v64
	v_log_f32_e32 v81, v64
	v_fma_f32 v64, v71, v69, v65
	v_log_f32_e32 v97, v64
	v_mul_f32_e32 v64, 0xbfb8aa3b, v83
	v_exp_f32_e32 v64, v64
	v_mul_f32_e32 v65, 0xbfb8aa3b, v84
	v_exp_f32_e32 v65, v65
	v_pk_add_f32 v[82:83], v[66:67], 1.0 op_sel_hi:[1,0] neg_lo:[1,0] neg_hi:[1,0]
	v_add_f32_e32 v64, 1.0, v64
	v_rcp_f32_e32 v64, v64
	v_add_f32_e32 v65, 1.0, v65
	v_rcp_f32_e32 v65, v65
	v_ashrrev_i32_e32 v88, 3, v95
	v_fma_f32 v66, v82, v64, v66
	v_log_f32_e32 v100, v66
	v_fmac_f32_e32 v67, v83, v65
	v_mul_f32_e32 v66, 0xbfb8aa3b, v85
	v_log_f32_e32 v101, v67
	v_exp_f32_e32 v66, v66
	v_mul_f32_e32 v67, 0xbfb8aa3b, v86
	v_exp_f32_e32 v67, v67
	v_pk_add_f32 v[84:85], v[60:61], 1.0 op_sel_hi:[1,0] neg_lo:[1,0] neg_hi:[1,0]
	v_add_f32_e32 v66, 1.0, v66
	v_rcp_f32_e32 v66, v66
	v_add_f32_e32 v67, 1.0, v67
	v_rcp_f32_e32 v67, v67
	v_and_b32_e32 v99, 56, v94
	v_fma_f32 v60, v84, v66, v60
	v_log_f32_e32 v102, v60
	v_fma_f32 v60, v85, v67, v61
	v_log_f32_e32 v103, v60
	v_mul_f32_e32 v60, 0xbfb8aa3b, v87
	v_mul_f32_e32 v61, 0xbfb8aa3b, v89
	v_exp_f32_e32 v60, v60
	v_exp_f32_e32 v61, v61
	v_pk_add_f32 v[86:87], v[62:63], 1.0 op_sel_hi:[1,0] neg_lo:[1,0] neg_hi:[1,0]
	s_movk_i32 s12, 0x104
	v_add_f32_e32 v60, 1.0, v60
	v_add_f32_e32 v61, 1.0, v61
	v_rcp_f32_e32 v60, v60
	v_rcp_f32_e32 v61, v61
	v_mul_lo_u32 v89, v88, s12
	v_lshlrev_b32_e32 v98, 2, v99
	v_fma_f32 v62, v86, v60, v62
	v_fmac_f32_e32 v63, v87, v61
	v_log_f32_e32 v62, v62
	v_log_f32_e32 v63, v63
	v_add3_u32 v98, 0, v89, v98
	ds_write2_b32 v98, v81, v97 offset1:1
	ds_write2_b32 v98, v100, v101 offset0:2 offset1:3
	ds_write2_b32 v98, v102, v103 offset0:4 offset1:5
	ds_write2_b32 v98, v62, v63 offset0:6 offset1:7
	v_mul_lo_u32 v62, v88, s10
	v_lshlrev_b32_e32 v63, 1, v99
	v_add3_u32 v97, 0, v62, v63
	ds_write_b128 v97, v[56:59] offset:46336
	v_mov_b32_e32 v81, v198
	s_waitcnt lgkmcnt(0)
	s_barrier
	s_movk_i32 s12, 0x820
	v_and_b32_e32 v57, 63, v81
	v_ashrrev_i32_e32 v56, 6, v81
	v_lshl_add_u32 v58, v57, 2, 0
	v_mul_lo_u32 v59, v56, s12
	v_add_u32_e32 v100, v58, v59
	ds_read2_b32 v[62:63], v100 offset1:65
	v_mov_b32_e32 v79, s23
	v_mov_b32_e32 v58, 0
	v_cmp_lt_i32_e32 vcc, 0, v56
	s_waitcnt lgkmcnt(0)
	v_add_f32_e32 v59, 0, v62
	v_add_f32_e32 v88, v59, v63
	ds_read2_b32 v[62:63], v100 offset0:130 offset1:195
	ds_write2_b32 v100, v59, v88 offset1:65
	s_waitcnt lgkmcnt(1)
	v_add_f32_e32 v59, v88, v62
	v_add_f32_e32 v88, v59, v63
	ds_write2_b32 v100, v59, v88 offset0:130 offset1:195
	v_add_u32_e32 v59, 0x400, v100
	ds_read2_b32 v[62:63], v59 offset0:4 offset1:69
	s_waitcnt lgkmcnt(0)
	v_add_f32_e32 v62, v88, v62
	v_add_f32_e32 v88, v62, v63
	ds_write2_b32 v59, v62, v88 offset0:4 offset1:69
	ds_read2_b32 v[62:63], v59 offset0:134 offset1:199
	s_waitcnt lgkmcnt(0)
	v_add_f32_e32 v62, v88, v62
	v_add_f32_e32 v63, v62, v63
	ds_write2_b32 v59, v62, v63 offset0:134 offset1:199
	v_lshl_add_u32 v62, v81, 2, 0
	ds_write_b32 v62, v63 offset:16640
	s_waitcnt lgkmcnt(0)
	s_barrier
	s_and_saveexec_b64 s[14:15], vcc
	s_cbranch_execz .LBB0_493
	v_readlane_b32 s12, v255, 12
	v_mov_b32_e32 v58, 0
	s_mov_b64 s[46:47], 0
	v_lshl_add_u32 v57, v57, 2, s12

; template <int WHICH>
; __device__ __forceinline__ HgRaw hg_load(KP& P_, int l, int u, int tid) {
;     const bf16_t* proj = (const bf16_t*)(p.ws + WS_PROJ);
;     const int idx = u - 780, bc = idx / 6, h = idx - bc * 6, t = tid >> 3, k0 = (tid & 7) * 8; const size_t row = (size_t)bc * 64 + t;
;     HgRaw r; r.q = (u32x4){0u, 0u, 0u, 0u};
;     if (WHICH) r.q = *(const u32x4*)(proj + row * NPROJ + h * 64 + k0);
;     r.f = *(const u32x4*)(proj + row * NPROJ + C_F + h * 64 + k0);
;     r.i = *(const u32x4*)(proj + row * NPROJ + C_I + h * 64 + k0);
;     const float* lbv = (const float*)(p.ws + TBL(T_LB, l)) + h * 64 + k0; r.lb0 = *(const f32x4*)lbv; r.lb1 = *(const f32x4*)(lbv + 4);
;     return r;
; template <int WHICH>
; __device__ void phase_mix_dyn(LAS unsigned char* lds, KP& P0, int l0) {
;     ...
;     HgRaw nxt; { KPtr P_ = P0; asm volatile("" : "+s"(P_.q)); nxt = hg_load<WHICH>(P_, l0, u, tid0); }
.LBB0_687:
	s_cmpk_gt_u32 s13, 0x923
	s_cbranch_scc1 .LBB0_708
	s_mov_b64 s[14:15], s[30:31]
	s_load_dwordx2 s[14:15], s[14:15], 0xe8
	s_add_i32 s12, s13, 0xfffffcf4
	s_mul_i32 s20, s12, 0xaaab
	s_lshr_b32 s20, s20, 18
	v_ashrrev_i32_e32 v2, 3, v100
	v_lshlrev_b32_e32 v0, 3, v100
	s_mul_i32 s21, s20, -6
	s_waitcnt vmcnt(7)
	v_and_b32_e32 v40, 56, v0
	v_lshl_add_u32 v0, s20, 6, v2
	s_waitcnt lgkmcnt(0)
	v_mov_b64_e32 v[8:9], s[14:15]
	s_add_i32 s12, s21, s12
	v_mad_i64_i32 v[8:9], s[20:21], v0, s9, v[8:9]
	s_lshl_b32 s20, s12, 6
	v_readlane_b32 s22, v255, 25
	s_ashr_i32 s21, s20, 31
	s_mul_hi_i32 s12, s22, 0x44800
	s_mul_i32 s22, s22, 0x44800
	s_add_u32 s22, s14, s22
	s_addc_u32 s12, s15, s12
	s_lshl_b64 s[14:15], s[20:21], 2
	v_lshl_add_u64 v[8:9], s[20:21], 1, v[8:9]
	v_lshlrev_b32_e32 v0, 1, v40
	s_add_u32 s14, s22, s14
	v_lshl_add_u64 v[8:9], v[8:9], 0, v[0:1]
	s_addc_u32 s15, s12, s15
	v_lshlrev_b32_e32 v0, 2, v40
	global_load_dwordx4 v[36:39], v[8:9], off offset:768
	global_load_dwordx4 v[24:27], v[8:9], off offset:1536
	v_lshl_add_u64 v[8:9], s[14:15], 0, v[0:1]
	s_mov_b64 s[14:15], 0xef04800
	v_lshl_add_u64 v[10:11], v[8:9], 0, s[14:15]
	v_add_co_u32_e32 v8, vcc, 0xef04000, v8
	v_ashrrev_i32_e32 v3, 31, v2
	s_nop 0
	v_addc_co_u32_e32 v9, vcc, 0, v9, vcc
	global_load_dwordx4 v[32:35], v[8:9], off offset:2048
	global_load_dwordx4 v[28:31], v[10:11], off offset:16
	v_readlane_b32 s23, v255, 26
	s_waitcnt vmcnt(0)
	s_load_dwordx2 s[72:73], s[30:31], 0xe8
	s_load_dwordx2 s[74:75], s[30:31], 0x20
	s_waitcnt lgkmcnt(0)
	s_branch .LBB0_691

; template <int WHICH>
; __device__ __forceinline__ HgRaw hg_load(KP& P_, int l, int u, int tid) {
;     const bf16_t* proj = (const bf16_t*)(p.ws + WS_PROJ);
;     const int idx = u - 780, bc = idx / 6, h = idx - bc * 6, t = tid >> 3, k0 = (tid & 7) * 8; const size_t row = (size_t)bc * 64 + t;
;     HgRaw r; r.q = (u32x4){0u, 0u, 0u, 0u};
;     if (WHICH) r.q = *(const u32x4*)(proj + row * NPROJ + h * 64 + k0);
;     r.f = *(const u32x4*)(proj + row * NPROJ + C_F + h * 64 + k0);
;     r.i = *(const u32x4*)(proj + row * NPROJ + C_I + h * 64 + k0);
;     const float* lbv = (const float*)(p.ws + TBL(T_LB, l)) + h * 64 + k0; r.lb0 = *(const f32x4*)lbv; r.lb1 = *(const f32x4*)(lbv + 4);
;     return r;
; }
.Lhg_tk_a:
	s_or_b64 exec, exec, s[44:45]
	v_mov_b64_e32 v[20:21], v[28:29]
	s_mov_b64 s[24:25], s[30:31]
	s_mov_b32 s12, s14
	s_and_b64 vcc, exec, s[20:21]
	v_mov_b64_e32 v[10:11], v[38:39]
	v_mov_b64_e32 v[14:15], v[26:27]
	v_mov_b64_e32 v[18:19], v[34:35]
	v_mov_b64_e32 v[22:23], v[30:31]
	v_readlane_b32 s15, v255, 26
	s_cbranch_vccnz .LBB0_697
	s_add_i32 s26, s62, 0xfffffcf4
	s_mul_hi_i32 s42, s26, 0x2aaaaaab
	s_mov_b64 s[14:15], s[72:73]
	s_lshr_b32 s43, s42, 31
	s_add_i32 s42, s42, s43
	s_mul_i32 s43, s42, -6
	s_add_i32 s26, s43, s26
	s_ashr_i32 s43, s42, 31
	s_lshl_b64 s[42:43], s[42:43], 6
	v_lshl_add_u64 v[8:9], s[42:43], 0, v[2:3]
	s_waitcnt lgkmcnt(0)
	v_mov_b64_e32 v[10:11], s[14:15]
	v_mad_u64_u32 v[10:11], s[42:43], v8, s9, v[10:11]
	s_lshl_b32 s42, s26, 6
	s_ashr_i32 s43, s42, 31
	s_mul_hi_i32 s26, s12, 0x44800
	s_mul_i32 s12, s12, 0x44800
	s_add_u32 s12, s14, s12
	v_mad_i32_i24 v11, v9, s9, v11
	s_addc_u32 s26, s15, s26
	s_lshl_b64 s[14:15], s[42:43], 2
	v_lshl_add_u64 v[8:9], s[42:43], 1, v[10:11]
	v_lshlrev_b32_e32 v0, 1, v40
	s_add_u32 s14, s12, s14
	v_lshl_add_u64 v[12:13], v[8:9], 0, v[0:1]
	s_addc_u32 s15, s26, s15
	v_lshlrev_b32_e32 v0, 2, v40
	v_lshl_add_u64 v[16:17], s[14:15], 0, v[0:1]
	s_mov_b64 s[14:15], 0xef04800
	v_lshl_add_u64 v[20:21], v[16:17], 0, s[14:15]
	v_add_co_u32_e32 v16, vcc, 0xef04000, v16
	global_load_dwordx4 v[8:11], v[12:13], off offset:768
	s_nop 0
	global_load_dwordx4 v[12:15], v[12:13], off offset:1536
	v_addc_co_u32_e32 v17, vcc, 0, v17, vcc
	global_load_dwordx4 v[16:19], v[16:17], off offset:2048
	s_nop 0
	global_load_dwordx4 v[20:23], v[20:21], off offset:16

; #define LAS __attribute__((address_space(3)))
; __device__ __forceinline__ u32x4 pack8(const float* o) { u32x4 v; v.x = cvt_pk_bf16(o[0], o[1]); v.y = cvt_pk_bf16(o[2], o[3]); v.z = cvt_pk_bf16(o[4], o[5]); v.w = cvt_pk_bf16(o[6], o[7]); return v; }
; __device__ __forceinline__ u32x2 pack4(const f32x4 a) { u32x2 v; v.x = cvt_pk_bf16(a[0], a[1]); v.y = cvt_pk_bf16(a[2], a[3]); return v; }
; #define LBAR() do { asm volatile("s_waitcnt lgkmcnt(0)" ::: "memory"); __builtin_amdgcn_s_barrier(); asm volatile("" ::: "memory"); } while (0)
; #define MFMA16(a, b, c) __builtin_amdgcn_mfma_f32_16x16x32_bf16((a), (b), (c), 0, 0, 0)
; __device__ __forceinline__ void hgrn_a_unit(LAS unsigned char* lds, KP& P_, int l, int bc, int h, const HgRaw& in) {
;     ...
;     cumsum64(Gf, seg);
;     { float kd[8];
; #pragma unroll
;       for (int j = 0; j < 8; ++j) { const float G = Gf[t * 65 + k0 + j], Gl = Gf[63 * 65 + k0 + j]; kd[j] = kk[j] * __builtin_amdgcn_exp2f(Gl - G); }
;       if (t == 63) { f32x4 d0, d1;
; #pragma unroll
;           for (int j = 0; j < 4; ++j) { d0[j] = __builtin_amdgcn_exp2f(Gf[63 * 65 + k0 + j]); d1[j] = __builtin_amdgcn_exp2f(Gf[63 * 65 + k0 + 4 + j]); }
;           float* dp = (float*)(p.ws + WS_DECH) + ((size_t)bc * 6 + h) * 64 + k0; *(f32x4*)dp = d0; *(f32x4*)(dp + 4) = d1; }
;       *(LAS u32x4*)(KT + t * 72 + k0) = pack8(kd); }
;     LBAR();
;     { const int wid = tid >> 6, lane = tid & 63, fr = lane & 15, fq = lane >> 4, kt = wid >> 1;
;       bf16_t* sth = (bf16_t*)(p.ws + WS_STH) + ((size_t)bc * 6 + h) * 4096;
; #pragma unroll
;       for (int q = 0; q < 2; ++q) { const int vt = (wid & 1) * 2 + q; f32x4 acc = (f32x4){0.f, 0.f, 0.f, 0.f};
; #pragma unroll
;           for (int ks = 0; ks < 2; ++ks) { const unsigned ro = (unsigned)((32 * ks + 8 * fq + (fr >> 2)) * 144 + 8 * (fr & 3));
;               const unsigned ka = (unsigned)(size_t)KT + ro + 32u * kt, va = (unsigned)(size_t)VT + ro + 32u * vt;
;               const bf16x8 a = tr_frag(ka, ka + 576u), b = tr_frag(va, va + 576u); acc = MFMA16(a, b, acc); }
;           *(u32x2*)(sth + (size_t)(vt * 16 + fr) * 64 + kt * 16 + fq * 4) = pack4(acc); } }
;     LBAR();
.LBB0_701:
	s_or_b64 exec, exec, s[14:15]
	ds_read2_b32 v[30:31], v24 offset1:65
	ds_read2_b32 v[50:51], v24 offset0:130 offset1:195
	s_add_i32 s14, s13, 0xfffffcf4
	s_mul_hi_i32 s12, s14, 0x2aaaaaab
	s_lshr_b32 s15, s12, 31
	s_waitcnt lgkmcnt(1)
	v_add_f32_e32 v27, v25, v30
	v_add_f32_e32 v30, v25, v31
	ds_write2_b32 v24, v27, v30 offset1:65
	ds_read2_b32 v[30:31], v26 offset0:4 offset1:69
	s_waitcnt lgkmcnt(2)
	v_add_f32_e32 v27, v25, v50
	v_add_f32_e32 v52, v25, v51
	ds_read2_b32 v[50:51], v26 offset0:134 offset1:199
	ds_write2_b32 v24, v27, v52 offset0:130 offset1:195
	s_waitcnt lgkmcnt(2)
	v_add_f32_e32 v24, v25, v30
	v_add_f32_e32 v27, v25, v31
	ds_write2_b32 v26, v24, v27 offset0:4 offset1:69
	s_waitcnt lgkmcnt(2)
	v_add_f32_e32 v24, v25, v50
	v_add_f32_e32 v25, v25, v51
	ds_write2_b32 v26, v24, v25 offset0:134 offset1:199
	v_lshl_add_u32 v26, v48, 2, 0
	s_waitcnt lgkmcnt(0)
	s_barrier
	v_add_u32_e32 v27, 0x3ffc, v26
	v_add_u32_e32 v48, 0x4004, v26
	v_add_u32_e32 v52, 0x400c, v26
	v_add_u32_e32 v56, 0x4014, v26
	ds_read2_b32 v[24:25], v49 offset1:1
	ds_read2_b32 v[30:31], v49 offset0:2 offset1:3
	ds_read2_b32 v[50:51], v49 offset0:4 offset1:5
	ds_read2_b32 v[54:55], v49 offset0:6 offset1:7
	ds_read2_b32 v[26:27], v27 offset1:1
	ds_read2_b32 v[48:49], v48 offset1:1
	ds_read2_b32 v[52:53], v52 offset1:1
	ds_read2_b32 v[56:57], v56 offset1:1
	s_add_i32 s15, s12, s15
	s_mul_i32 s12, s15, 6
	s_sub_i32 s26, s14, s12
	v_cmp_ne_u32_e32 vcc, 63, v58
	s_mul_hi_i32 s44, s15, 6
	s_and_saveexec_b64 s[42:43], vcc
	s_xor_b64 s[42:43], exec, s[42:43]
	s_ashr_i32 s15, s26, 31
	s_add_u32 s14, s12, s26
	s_addc_u32 s15, s44, s15
	s_or_saveexec_b64 s[42:43], s[42:43]
	v_mov_b64_e32 v[58:59], s[14:15]
	s_xor_b64 exec, exec, s[42:43]
	s_cbranch_execz .LBB0_705
	s_mov_b64 s[14:15], s[72:73]
	s_ashr_i32 s45, s26, 31
	s_add_u32 s46, s12, s26
	s_addc_u32 s47, s44, s45
	s_lshl_b64 s[44:45], s[46:47], 8
	s_waitcnt lgkmcnt(0)
	s_add_u32 s14, s14, s44
	v_exp_f32_e32 v62, v26
	v_exp_f32_e32 v63, v27
	v_exp_f32_e32 v64, v48
	v_exp_f32_e32 v65, v49
	s_addc_u32 s15, s15, s45
	v_exp_f32_e32 v66, v52
	v_exp_f32_e32 v67, v53
	v_exp_f32_e32 v68, v56
	v_exp_f32_e32 v69, v57
	v_lshl_add_u64 v[58:59], s[14:15], 0, v[0:1]
	s_mov_b64 s[14:15], 0xe998000
	v_lshl_add_u64 v[70:71], v[58:59], 0, s[14:15]
	v_add_co_u32_e32 v58, vcc, 0xe998000, v58
	s_nop 1
	v_addc_co_u32_e32 v59, vcc, 0, v59, vcc
	global_store_dwordx4 v[58:59], v[62:65], off
	global_store_dwordx4 v[70:71], v[66:69], off offset:16
	v_mov_b64_e32 v[58:59], s[46:47]
.LBB0_705:
	s_or_b64 exec, exec, s[42:43]
	s_waitcnt lgkmcnt(0)
	v_sub_f32_e32 v0, v57, v55
	v_exp_f32_e32 v55, v0
	v_sub_f32_e32 v0, v56, v54
	v_pk_add_f32 v[46:47], v[46:47], 1.0 op_sel_hi:[1,0] neg_lo:[1,0] neg_hi:[1,0]
	v_exp_f32_e32 v54, v0
	v_sub_f32_e32 v0, v53, v51
	v_pk_mul_f32 v[28:29], v[28:29], v[46:47]
	v_exp_f32_e32 v47, v0
	v_sub_f32_e32 v0, v52, v50
	v_exp_f32_e32 v46, v0
	v_sub_f32_e32 v0, v49, v31
	v_exp_f32_e32 v31, v0
	v_sub_f32_e32 v0, v48, v30
	v_exp_f32_e32 v30, v0
	v_sub_f32_e32 v0, v27, v25
	v_exp_f32_e32 v25, v0
	v_sub_f32_e32 v0, v26, v24
	v_pk_add_f32 v[42:43], v[42:43], 1.0 op_sel_hi:[1,0] neg_lo:[1,0] neg_hi:[1,0]
	v_exp_f32_e32 v24, v0
	v_pk_mul_f32 v[32:33], v[32:33], v[42:43]
	v_pk_add_f32 v[34:35], v[34:35], 1.0 op_sel_hi:[1,0] neg_lo:[1,0] neg_hi:[1,0]
	v_pk_mul_f32 v[26:27], v[32:33], v[30:31]
	v_pk_add_f32 v[30:31], v[36:37], 1.0 op_sel_hi:[1,0] neg_lo:[1,0] neg_hi:[1,0]
	v_pk_mul_f32 v[34:35], v[44:45], v[34:35]
	v_pk_mul_f32 v[30:31], v[38:39], v[30:31]
	v_pk_mul_f32 v[28:29], v[28:29], v[54:55]
	v_pk_mul_f32 v[34:35], v[34:35], v[46:47]
	v_pk_mul_f32 v[24:25], v[30:31], v[24:25]
	v_lshrrev_b32_e32 v0, 5, v60
	v_cvt_pk_bf16_f32 v24, v24, v25
	v_cvt_pk_bf16_f32 v25, v26, v27
	v_cvt_pk_bf16_f32 v26, v34, v35
	v_cvt_pk_bf16_f32 v27, v28, v29
	ds_write_b128 v61, v[24:27] offset:18688
	s_waitcnt lgkmcnt(0)
	s_barrier
	s_mov_b64 s[14:15], s[72:73]
	v_ashrrev_i32_e32 v26, 7, v60
	v_and_b32_e32 v39, 2, v0
	v_lshrrev_b32_e32 v0, 1, v60
	v_readlane_b32 s12, v255, 15
	v_lshlrev_b64 v[24:25], 13, v[58:59]
	v_and_b32_e32 v0, 24, v0
	v_bfe_u32 v27, v60, 2, 2
	v_lshl_add_u32 v32, v26, 5, s12
	v_lshlrev_b32_e32 v26, 4, v26
	s_waitcnt lgkmcnt(0)
	v_lshl_add_u64 v[24:25], s[14:15], 0, v[24:25]
	v_or_b32_e32 v28, v0, v27
	v_and_b32_e32 v29, 24, v41
	v_ashrrev_i32_e32 v27, 31, v26
	v_lshl_add_u64 v[24:25], v[26:27], 1, v[24:25]
	v_mad_u32_u24 v41, v28, s10, v29
	v_readlane_b32 s12, v255, 16
	v_lshl_add_u64 v[24:25], v[24:25], 0, v[0:1]
	s_mov_b64 s[14:15], 0xc300000
	v_add_u32_e32 v42, v41, v32
	v_lshl_add_u32 v0, v39, 5, s12
	v_lshl_add_u64 v[36:37], v[24:25], 0, s[14:15]
	v_add_u32_e32 v33, v41, v0
	v_add_u32_e32 v43, 0x240, v42
	ds_read_b64_tr_b16 v[24:25], v42
	ds_read_b64_tr_b16 v[26:27], v43
	s_waitcnt lgkmcnt(0)
	v_add_u32_e32 v34, 0x240, v33
	ds_read_b64_tr_b16 v[28:29], v33
	ds_read_b64_tr_b16 v[30:31], v34
	s_waitcnt lgkmcnt(0)
	v_add_u32_e32 v44, 0x1200, v41
	v_mfma_f32_16x16x32_bf16 v[24:27], v[24:27], v[28:31], 0
	v_add_u32_e32 v45, v44, v32
	v_add_u32_e32 v0, v44, v0
	v_add_u32_e32 v46, 0x240, v45
	ds_read_b64_tr_b16 v[28:29], v45
	ds_read_b64_tr_b16 v[30:31], v46
	s_waitcnt lgkmcnt(0)
	v_add_u32_e32 v47, 0x240, v0
	ds_read_b64_tr_b16 v[32:33], v0
	ds_read_b64_tr_b16 v[34:35], v47
	s_waitcnt lgkmcnt(0)
	v_and_b32_e32 v38, 15, v60
	v_mfma_f32_16x16x32_bf16 v[24:27], v[28:31], v[32:35], v[24:27]
	v_lshlrev_b32_e32 v38, 7, v38
	v_lshl_or_b32 v0, v39, 11, v38
	s_andn2_b64 vcc, exec, s[22:23]
	s_nop 4
	v_cvt_pk_bf16_f32 v24, v24, v25
	v_cvt_pk_bf16_f32 v25, v26, v27
	v_lshl_add_u64 v[26:27], v[36:37], 0, v[0:1]
	v_or_b32_e32 v0, 1, v39
	global_store_dwordx2 v[26:27], v[24:25], off
	v_lshl_add_u32 v32, v0, 5, s12
	v_add_u32_e32 v33, v41, v32
	ds_read_b64_tr_b16 v[24:25], v42
	ds_read_b64_tr_b16 v[26:27], v43
	s_waitcnt lgkmcnt(0)
	v_add_u32_e32 v34, 0x240, v33
	ds_read_b64_tr_b16 v[28:29], v33
	ds_read_b64_tr_b16 v[30:31], v34
	s_waitcnt lgkmcnt(0)
	v_add_u32_e32 v39, v44, v32
	v_mfma_f32_16x16x32_bf16 v[24:27], v[24:27], v[28:31], 0
	ds_read_b64_tr_b16 v[28:29], v45
	ds_read_b64_tr_b16 v[30:31], v46
	s_waitcnt lgkmcnt(0)
	v_add_u32_e32 v41, 0x240, v39
	ds_read_b64_tr_b16 v[32:33], v39
	ds_read_b64_tr_b16 v[34:35], v41
	s_waitcnt lgkmcnt(0)
	v_lshl_or_b32 v0, v0, 11, v38
	v_mfma_f32_16x16x32_bf16 v[24:27], v[28:31], v[32:35], v[24:27]
	s_nop 7
	v_cvt_pk_bf16_f32 v24, v24, v25
	v_cvt_pk_bf16_f32 v25, v26, v27
	v_lshl_add_u64 v[26:27], v[36:37], 0, v[0:1]
	global_store_dwordx2 v[26:27], v[24:25], off
	s_waitcnt lgkmcnt(0)
	s_barrier
	s_cbranch_vccnz .LBB0_690
	s_and_saveexec_b64 s[14:15], s[40:41]
	s_cbranch_execz .LBB0_689
	s_waitcnt vmcnt(0)
	v_readlane_b32 s12, v255, 7
	s_nop 1
	v_mov_b32_e32 v0, s12
	v_readlane_b32 s12, v255, 8
	ds_write_b32 v0, v99
	s_nop 0
	v_mov_b32_e32 v0, s12
	ds_write_b32 v0, v98
	s_branch .LBB0_689
